# SwiGLU epilogue of both gate/up GEMMs regenerated with packed f32 ops: out = (g*u) * rcp(1+exp2(g*(-log2e*r))) * r^2, 42 VALU per 8 outputs instead of 60 (v12 base)
# speedup vs baseline: 1.0070x; 1.0070x over previous
; __device__ __forceinline__ unsigned cvt_pk_bf16(float lo, float hi) { unsigned r; asm volatile("v_cvt_pk_bf16_f32 %0, %1, %2" : "=v"(r) : "v"(lo), "v"(hi)); return r; }
; __device__ __forceinline__ float silu_f(float g) { return g * __builtin_amdgcn_rcpf(1.0f + __expf(-g)); }
; __device__ __forceinline__ float row_rstd(const float* rss, int row) { if (!rss) return 1.0f; const f32x4 s = *(const f32x4*)(rss + 4 * (size_t)row); return __builtin_amdgcn_rsqf(((s[0] + s[1]) + (s[2] + s[3])) * (1.0f / 1024.0f) + 1e-6f); }
;     __device__ __forceinline__ void operator()(const f32x4 (&acc)[2][2][4][2], const Unit& u, int wr, int wc, int fr, int fq) const {
;     ...
;             for (int m = 0; m < 4; ++m) { const int row = row0 + ai * HALF + m * 16; bf16_t* rowp = O + (size_t)row * ldc + col0; const float rs = row_rstd(rss, row);
;                 const f32x4 g0 = acc[ai][0][m][0] * rs, g1 = acc[ai][0][m][1] * rs, u0 = acc[ai][1][m][0] * rs, u1 = acc[ai][1][m][1] * rs;
;                 u32x4 w;
;                 w.x = cvt_pk_bf16(silu_f(g0[0]) * u0[0], silu_f(g0[1]) * u0[1]); w.y = cvt_pk_bf16(silu_f(g0[2]) * u0[2], silu_f(g0[3]) * u0[3]);
;                 w.z = cvt_pk_bf16(silu_f(g1[0]) * u1[0], silu_f(g1[1]) * u1[1]); w.w = cvt_pk_bf16(silu_f(g1[2]) * u1[2], silu_f(g1[3]) * u1[3]);
;                 *(u32x4*)rowp = w; }
.LBB0_211:
	v_lshl_or_b32 v148, s0, 7, v159
	v_lshl_add_u32 v150, s1, 8, v1
	v_ashrrev_i32_e32 v149, 31, v148
	v_mov_b64_e32 v[146:147], s[20:21]
	v_ashrrev_i32_e32 v151, 31, v150
	v_mad_i64_i32 v[162:163], s[0:1], v150, s4, v[146:147]
	v_lshlrev_b64 v[148:149], 1, v[148:149]
	v_lshl_add_u64 v[166:167], v[162:163], 0, v[148:149]
	v_lshl_add_u64 v[162:163], v[150:151], 4, s[22:23]
	global_load_dwordx4 v[162:165], v[162:163], off
	s_mov_b64 s[30:31], -1
	s_and_b64 vcc, exec, s[8:9]
	s_waitcnt vmcnt(0)
	v_mov_b32_e32 v168, v163
	v_mov_b32_e32 v169, v164
	v_mov_b32_e32 v163, v165
	v_pk_add_f32 v[162:163], v[168:169], v[162:163]
	s_nop 0
	v_add_f32_e32 v151, v162, v163
	v_fmamk_f32 v151, v151, 0x3a800000, v138
	v_rsq_f32_e32 v162, v151
	s_nop 0
	v_mul_f32_e32 v198, 0xbfb8aa3b, v162
	v_mul_f32_e32 v200, v162, v162
	v_mov_b32_e32 v202, 1.0
	v_pk_mul_f32 v[182:183], v[122:123], v[198:199] op_sel_hi:[1,0]
	v_pk_mul_f32 v[186:187], v[124:125], v[198:199] op_sel_hi:[1,0]
	v_pk_mul_f32 v[190:191], v[126:127], v[198:199] op_sel_hi:[1,0]
	v_pk_mul_f32 v[194:195], v[128:129], v[198:199] op_sel_hi:[1,0]
	v_exp_f32_e32 v182, v182
	v_exp_f32_e32 v183, v183
	v_exp_f32_e32 v186, v186
	v_exp_f32_e32 v187, v187
	v_exp_f32_e32 v190, v190
	v_exp_f32_e32 v191, v191
	v_exp_f32_e32 v194, v194
	v_exp_f32_e32 v195, v195
	v_pk_mul_f32 v[184:185], v[122:123], v[118:119]
	v_pk_mul_f32 v[188:189], v[124:125], v[120:121]
	v_pk_mul_f32 v[192:193], v[126:127], v[114:115]
	v_pk_mul_f32 v[196:197], v[128:129], v[116:117]
	v_pk_add_f32 v[182:183], v[182:183], v[202:203] op_sel_hi:[1,0]
	v_pk_add_f32 v[186:187], v[186:187], v[202:203] op_sel_hi:[1,0]
	v_pk_add_f32 v[190:191], v[190:191], v[202:203] op_sel_hi:[1,0]
	v_pk_add_f32 v[194:195], v[194:195], v[202:203] op_sel_hi:[1,0]
	v_rcp_f32_e32 v182, v182
	v_rcp_f32_e32 v183, v183
	v_rcp_f32_e32 v186, v186
	v_rcp_f32_e32 v187, v187
	v_rcp_f32_e32 v190, v190
	v_rcp_f32_e32 v191, v191
	v_rcp_f32_e32 v194, v194
	v_rcp_f32_e32 v195, v195
	v_pk_mul_f32 v[184:185], v[184:185], v[200:201] op_sel_hi:[1,0]
	v_pk_mul_f32 v[188:189], v[188:189], v[200:201] op_sel_hi:[1,0]
	v_pk_mul_f32 v[192:193], v[192:193], v[200:201] op_sel_hi:[1,0]
	v_pk_mul_f32 v[196:197], v[196:197], v[200:201] op_sel_hi:[1,0]
	v_pk_mul_f32 v[184:185], v[184:185], v[182:183]
	v_pk_mul_f32 v[188:189], v[188:189], v[186:187]
	v_pk_mul_f32 v[192:193], v[192:193], v[190:191]
	v_pk_mul_f32 v[196:197], v[196:197], v[194:195]
	v_cvt_pk_bf16_f32 v114, v184, v185
	v_cvt_pk_bf16_f32 v115, v188, v189
	v_cvt_pk_bf16_f32 v116, v192, v193
	v_cvt_pk_bf16_f32 v117, v196, v197
	global_store_dwordx4 v[166:167], v[114:117], off
	s_nop 1
	v_or_b32_e32 v116, 16, v150
	v_ashrrev_i32_e32 v117, 31, v116
	v_mad_i64_i32 v[114:115], s[0:1], v116, s4, v[146:147]
	v_lshl_add_u64 v[116:117], v[116:117], 4, s[22:23]
	global_load_dwordx4 v[116:119], v[116:117], off
	v_lshl_add_u64 v[114:115], v[114:115], 0, v[148:149]
	s_waitcnt vmcnt(0)
	v_mov_b32_e32 v120, v117
	v_mov_b32_e32 v121, v118
	v_mov_b32_e32 v117, v119
	v_pk_add_f32 v[116:117], v[120:121], v[116:117]
	s_nop 0
	v_add_f32_e32 v116, v116, v117
	v_fmamk_f32 v116, v116, 0x3a800000, v138
	v_rsq_f32_e32 v116, v116
	s_nop 0
	v_mul_f32_e32 v198, 0xbfb8aa3b, v116
	v_mul_f32_e32 v200, v116, v116
	v_mov_b32_e32 v202, 1.0
	v_pk_mul_f32 v[182:183], v[110:111], v[198:199] op_sel_hi:[1,0]
	v_pk_mul_f32 v[186:187], v[112:113], v[198:199] op_sel_hi:[1,0]
	v_pk_mul_f32 v[190:191], v[106:107], v[198:199] op_sel_hi:[1,0]
	v_pk_mul_f32 v[194:195], v[108:109], v[198:199] op_sel_hi:[1,0]
	v_exp_f32_e32 v182, v182
	v_exp_f32_e32 v183, v183
	v_exp_f32_e32 v186, v186
	v_exp_f32_e32 v187, v187
	v_exp_f32_e32 v190, v190
	v_exp_f32_e32 v191, v191
	v_exp_f32_e32 v194, v194
	v_exp_f32_e32 v195, v195
	v_pk_mul_f32 v[184:185], v[110:111], v[102:103]
	v_pk_mul_f32 v[188:189], v[112:113], v[104:105]
	v_pk_mul_f32 v[192:193], v[106:107], v[98:99]
	v_pk_mul_f32 v[196:197], v[108:109], v[100:101]
	v_pk_add_f32 v[182:183], v[182:183], v[202:203] op_sel_hi:[1,0]
	v_pk_add_f32 v[186:187], v[186:187], v[202:203] op_sel_hi:[1,0]
	v_pk_add_f32 v[190:191], v[190:191], v[202:203] op_sel_hi:[1,0]
	v_pk_add_f32 v[194:195], v[194:195], v[202:203] op_sel_hi:[1,0]
	v_rcp_f32_e32 v182, v182
	v_rcp_f32_e32 v183, v183
	v_rcp_f32_e32 v186, v186
	v_rcp_f32_e32 v187, v187
	v_rcp_f32_e32 v190, v190
	v_rcp_f32_e32 v191, v191
	v_rcp_f32_e32 v194, v194
	v_rcp_f32_e32 v195, v195
	v_pk_mul_f32 v[184:185], v[184:185], v[200:201] op_sel_hi:[1,0]
	v_pk_mul_f32 v[188:189], v[188:189], v[200:201] op_sel_hi:[1,0]
	v_pk_mul_f32 v[192:193], v[192:193], v[200:201] op_sel_hi:[1,0]
	v_pk_mul_f32 v[196:197], v[196:197], v[200:201] op_sel_hi:[1,0]
	v_pk_mul_f32 v[184:185], v[184:185], v[182:183]
	v_pk_mul_f32 v[188:189], v[188:189], v[186:187]
	v_pk_mul_f32 v[192:193], v[192:193], v[190:191]
	v_pk_mul_f32 v[196:197], v[196:197], v[194:195]
	v_cvt_pk_bf16_f32 v98, v184, v185
	v_cvt_pk_bf16_f32 v99, v188, v189
	v_cvt_pk_bf16_f32 v100, v192, v193
	v_cvt_pk_bf16_f32 v101, v196, v197
	global_store_dwordx4 v[114:115], v[98:101], off
	s_nop 1
	v_or_b32_e32 v100, 32, v150
	v_ashrrev_i32_e32 v101, 31, v100
	v_mad_i64_i32 v[98:99], s[0:1], v100, s4, v[146:147]
	v_lshl_add_u64 v[100:101], v[100:101], 4, s[22:23]
	global_load_dwordx4 v[100:103], v[100:101], off
	v_lshl_add_u64 v[98:99], v[98:99], 0, v[148:149]
	s_waitcnt vmcnt(0)
; __device__ __forceinline__ unsigned cvt_pk_bf16(float lo, float hi) { unsigned r; asm volatile("v_cvt_pk_bf16_f32 %0, %1, %2" : "=v"(r) : "v"(lo), "v"(hi)); return r; }
; __device__ __forceinline__ float silu_f(float g) { return g * __builtin_amdgcn_rcpf(1.0f + __expf(-g)); }
; __device__ __forceinline__ float row_rstd(const float* rss, int row) { if (!rss) return 1.0f; const f32x4 s = *(const f32x4*)(rss + 4 * (size_t)row); return __builtin_amdgcn_rsqf(((s[0] + s[1]) + (s[2] + s[3])) * (1.0f / 1024.0f) + 1e-6f); }
;     __device__ __forceinline__ void operator()(const f32x4 (&acc)[2][2][4][2], const Unit& u, int wr, int wc, int fr, int fq) const {
;     ...
;             for (int m = 0; m < 4; ++m) { const int row = row0 + ai * HALF + m * 16; bf16_t* rowp = O + (size_t)row * ldc + col0; const float rs = row_rstd(rss, row);
;                 const f32x4 g0 = acc[ai][0][m][0] * rs, g1 = acc[ai][0][m][1] * rs, u0 = acc[ai][1][m][0] * rs, u1 = acc[ai][1][m][1] * rs;
;                 u32x4 w;
;                 w.x = cvt_pk_bf16(silu_f(g0[0]) * u0[0], silu_f(g0[1]) * u0[1]); w.y = cvt_pk_bf16(silu_f(g0[2]) * u0[2], silu_f(g0[3]) * u0[3]);
;                 w.z = cvt_pk_bf16(silu_f(g1[0]) * u1[0], silu_f(g1[1]) * u1[1]); w.w = cvt_pk_bf16(silu_f(g1[2]) * u1[2], silu_f(g1[3]) * u1[3]);
;                 *(u32x4*)rowp = w; }
	v_mov_b32_e32 v104, v101
	v_mov_b32_e32 v105, v102
	v_mov_b32_e32 v101, v103
	v_pk_add_f32 v[100:101], v[104:105], v[100:101]
	s_nop 0
	v_add_f32_e32 v100, v100, v101
	v_fmamk_f32 v100, v100, 0x3a800000, v138
	v_rsq_f32_e32 v100, v100
	s_nop 0
	v_mul_f32_e32 v198, 0xbfb8aa3b, v100
	v_mul_f32_e32 v200, v100, v100
	v_mov_b32_e32 v202, 1.0
	v_pk_mul_f32 v[182:183], v[94:95], v[198:199] op_sel_hi:[1,0]
	v_pk_mul_f32 v[186:187], v[96:97], v[198:199] op_sel_hi:[1,0]
	v_pk_mul_f32 v[190:191], v[90:91], v[198:199] op_sel_hi:[1,0]
	v_pk_mul_f32 v[194:195], v[92:93], v[198:199] op_sel_hi:[1,0]
	v_exp_f32_e32 v182, v182
	v_exp_f32_e32 v183, v183
	v_exp_f32_e32 v186, v186
	v_exp_f32_e32 v187, v187
	v_exp_f32_e32 v190, v190
	v_exp_f32_e32 v191, v191
	v_exp_f32_e32 v194, v194
	v_exp_f32_e32 v195, v195
	v_pk_mul_f32 v[184:185], v[94:95], v[86:87]
	v_pk_mul_f32 v[188:189], v[96:97], v[88:89]
	v_pk_mul_f32 v[192:193], v[90:91], v[82:83]
	v_pk_mul_f32 v[196:197], v[92:93], v[84:85]
	v_pk_add_f32 v[182:183], v[182:183], v[202:203] op_sel_hi:[1,0]
	v_pk_add_f32 v[186:187], v[186:187], v[202:203] op_sel_hi:[1,0]
	v_pk_add_f32 v[190:191], v[190:191], v[202:203] op_sel_hi:[1,0]
	v_pk_add_f32 v[194:195], v[194:195], v[202:203] op_sel_hi:[1,0]
	v_rcp_f32_e32 v182, v182
	v_rcp_f32_e32 v183, v183
	v_rcp_f32_e32 v186, v186
	v_rcp_f32_e32 v187, v187
	v_rcp_f32_e32 v190, v190
	v_rcp_f32_e32 v191, v191
	v_rcp_f32_e32 v194, v194
	v_rcp_f32_e32 v195, v195
	v_pk_mul_f32 v[184:185], v[184:185], v[200:201] op_sel_hi:[1,0]
	v_pk_mul_f32 v[188:189], v[188:189], v[200:201] op_sel_hi:[1,0]
	v_pk_mul_f32 v[192:193], v[192:193], v[200:201] op_sel_hi:[1,0]
	v_pk_mul_f32 v[196:197], v[196:197], v[200:201] op_sel_hi:[1,0]
	v_pk_mul_f32 v[184:185], v[184:185], v[182:183]
	v_pk_mul_f32 v[188:189], v[188:189], v[186:187]
	v_pk_mul_f32 v[192:193], v[192:193], v[190:191]
	v_pk_mul_f32 v[196:197], v[196:197], v[194:195]
	v_cvt_pk_bf16_f32 v82, v184, v185
	v_cvt_pk_bf16_f32 v83, v188, v189
	v_cvt_pk_bf16_f32 v84, v192, v193
	v_cvt_pk_bf16_f32 v85, v196, v197
	global_store_dwordx4 v[98:99], v[82:85], off
	s_nop 1
	v_or_b32_e32 v84, 48, v150
	v_ashrrev_i32_e32 v85, 31, v84
	v_mad_i64_i32 v[82:83], s[0:1], v84, s4, v[146:147]
	v_lshl_add_u64 v[84:85], v[84:85], 4, s[22:23]
	global_load_dwordx4 v[84:87], v[84:85], off
	v_lshl_add_u64 v[82:83], v[82:83], 0, v[148:149]
	s_waitcnt vmcnt(0)
	v_mov_b32_e32 v88, v85
	v_mov_b32_e32 v89, v86
	v_mov_b32_e32 v85, v87
	v_pk_add_f32 v[84:85], v[88:89], v[84:85]
	s_nop 0
	v_add_f32_e32 v84, v84, v85
	v_fmamk_f32 v84, v84, 0x3a800000, v138
	v_rsq_f32_e32 v84, v84
	s_nop 0
	v_mul_f32_e32 v198, 0xbfb8aa3b, v84
	v_mul_f32_e32 v200, v84, v84
	v_mov_b32_e32 v202, 1.0
	v_pk_mul_f32 v[182:183], v[78:79], v[198:199] op_sel_hi:[1,0]
	v_pk_mul_f32 v[186:187], v[80:81], v[198:199] op_sel_hi:[1,0]
	v_pk_mul_f32 v[190:191], v[74:75], v[198:199] op_sel_hi:[1,0]
	v_pk_mul_f32 v[194:195], v[76:77], v[198:199] op_sel_hi:[1,0]
	v_exp_f32_e32 v182, v182
	v_exp_f32_e32 v183, v183
	v_exp_f32_e32 v186, v186
	v_exp_f32_e32 v187, v187
	v_exp_f32_e32 v190, v190
	v_exp_f32_e32 v191, v191
	v_exp_f32_e32 v194, v194
	v_exp_f32_e32 v195, v195
	v_pk_mul_f32 v[184:185], v[78:79], v[70:71]
	v_pk_mul_f32 v[188:189], v[80:81], v[72:73]
	v_pk_mul_f32 v[192:193], v[74:75], v[66:67]
	v_pk_mul_f32 v[196:197], v[76:77], v[68:69]
	v_pk_add_f32 v[182:183], v[182:183], v[202:203] op_sel_hi:[1,0]
	v_pk_add_f32 v[186:187], v[186:187], v[202:203] op_sel_hi:[1,0]
	v_pk_add_f32 v[190:191], v[190:191], v[202:203] op_sel_hi:[1,0]
	v_pk_add_f32 v[194:195], v[194:195], v[202:203] op_sel_hi:[1,0]
	v_rcp_f32_e32 v182, v182
	v_rcp_f32_e32 v183, v183
	v_rcp_f32_e32 v186, v186
	v_rcp_f32_e32 v187, v187
	v_rcp_f32_e32 v190, v190
	v_rcp_f32_e32 v191, v191
	v_rcp_f32_e32 v194, v194
	v_rcp_f32_e32 v195, v195
	v_pk_mul_f32 v[184:185], v[184:185], v[200:201] op_sel_hi:[1,0]
	v_pk_mul_f32 v[188:189], v[188:189], v[200:201] op_sel_hi:[1,0]
	v_pk_mul_f32 v[192:193], v[192:193], v[200:201] op_sel_hi:[1,0]
	v_pk_mul_f32 v[196:197], v[196:197], v[200:201] op_sel_hi:[1,0]
	v_pk_mul_f32 v[184:185], v[184:185], v[182:183]
	v_pk_mul_f32 v[188:189], v[188:189], v[186:187]
	v_pk_mul_f32 v[192:193], v[192:193], v[190:191]
	v_pk_mul_f32 v[196:197], v[196:197], v[194:195]
	v_cvt_pk_bf16_f32 v66, v184, v185
	v_cvt_pk_bf16_f32 v67, v188, v189
	v_cvt_pk_bf16_f32 v68, v192, v193
	v_cvt_pk_bf16_f32 v69, v196, v197
	global_store_dwordx4 v[82:83], v[66:69], off
	s_nop 1
	v_add_u32_e32 v68, 0x80, v150
	v_ashrrev_i32_e32 v69, 31, v68
	v_mad_i64_i32 v[66:67], s[0:1], v68, s4, v[146:147]
	v_lshl_add_u64 v[68:69], v[68:69], 4, s[22:23]
	global_load_dwordx4 v[68:71], v[68:69], off
	v_lshl_add_u64 v[66:67], v[66:67], 0, v[148:149]
	s_waitcnt vmcnt(0)
; __device__ __forceinline__ unsigned cvt_pk_bf16(float lo, float hi) { unsigned r; asm volatile("v_cvt_pk_bf16_f32 %0, %1, %2" : "=v"(r) : "v"(lo), "v"(hi)); return r; }
; __device__ __forceinline__ float silu_f(float g) { return g * __builtin_amdgcn_rcpf(1.0f + __expf(-g)); }
; __device__ __forceinline__ float row_rstd(const float* rss, int row) { if (!rss) return 1.0f; const f32x4 s = *(const f32x4*)(rss + 4 * (size_t)row); return __builtin_amdgcn_rsqf(((s[0] + s[1]) + (s[2] + s[3])) * (1.0f / 1024.0f) + 1e-6f); }
;     __device__ __forceinline__ void operator()(const f32x4 (&acc)[2][2][4][2], const Unit& u, int wr, int wc, int fr, int fq) const {
;     ...
;             for (int m = 0; m < 4; ++m) { const int row = row0 + ai * HALF + m * 16; bf16_t* rowp = O + (size_t)row * ldc + col0; const float rs = row_rstd(rss, row);
;                 const f32x4 g0 = acc[ai][0][m][0] * rs, g1 = acc[ai][0][m][1] * rs, u0 = acc[ai][1][m][0] * rs, u1 = acc[ai][1][m][1] * rs;
;                 u32x4 w;
;                 w.x = cvt_pk_bf16(silu_f(g0[0]) * u0[0], silu_f(g0[1]) * u0[1]); w.y = cvt_pk_bf16(silu_f(g0[2]) * u0[2], silu_f(g0[3]) * u0[3]);
;                 w.z = cvt_pk_bf16(silu_f(g1[0]) * u1[0], silu_f(g1[1]) * u1[1]); w.w = cvt_pk_bf16(silu_f(g1[2]) * u1[2], silu_f(g1[3]) * u1[3]);
;                 *(u32x4*)rowp = w; }
	v_mov_b32_e32 v72, v69
	v_mov_b32_e32 v73, v70
	v_mov_b32_e32 v69, v71
	v_pk_add_f32 v[68:69], v[72:73], v[68:69]
	s_nop 0
	v_add_f32_e32 v68, v68, v69
	v_fmamk_f32 v68, v68, 0x3a800000, v138
	v_rsq_f32_e32 v68, v68
	s_nop 0
	v_mul_f32_e32 v198, 0xbfb8aa3b, v68
	v_mul_f32_e32 v200, v68, v68
	v_mov_b32_e32 v202, 1.0
	v_pk_mul_f32 v[182:183], v[62:63], v[198:199] op_sel_hi:[1,0]
	v_pk_mul_f32 v[186:187], v[64:65], v[198:199] op_sel_hi:[1,0]
	v_pk_mul_f32 v[190:191], v[58:59], v[198:199] op_sel_hi:[1,0]
	v_pk_mul_f32 v[194:195], v[60:61], v[198:199] op_sel_hi:[1,0]
	v_exp_f32_e32 v182, v182
	v_exp_f32_e32 v183, v183
	v_exp_f32_e32 v186, v186
	v_exp_f32_e32 v187, v187
	v_exp_f32_e32 v190, v190
	v_exp_f32_e32 v191, v191
	v_exp_f32_e32 v194, v194
	v_exp_f32_e32 v195, v195
	v_pk_mul_f32 v[184:185], v[62:63], v[54:55]
	v_pk_mul_f32 v[188:189], v[64:65], v[56:57]
	v_pk_mul_f32 v[192:193], v[58:59], v[50:51]
	v_pk_mul_f32 v[196:197], v[60:61], v[52:53]
	v_pk_add_f32 v[182:183], v[182:183], v[202:203] op_sel_hi:[1,0]
	v_pk_add_f32 v[186:187], v[186:187], v[202:203] op_sel_hi:[1,0]
	v_pk_add_f32 v[190:191], v[190:191], v[202:203] op_sel_hi:[1,0]
	v_pk_add_f32 v[194:195], v[194:195], v[202:203] op_sel_hi:[1,0]
	v_rcp_f32_e32 v182, v182
	v_rcp_f32_e32 v183, v183
	v_rcp_f32_e32 v186, v186
	v_rcp_f32_e32 v187, v187
	v_rcp_f32_e32 v190, v190
	v_rcp_f32_e32 v191, v191
	v_rcp_f32_e32 v194, v194
	v_rcp_f32_e32 v195, v195
	v_pk_mul_f32 v[184:185], v[184:185], v[200:201] op_sel_hi:[1,0]
	v_pk_mul_f32 v[188:189], v[188:189], v[200:201] op_sel_hi:[1,0]
	v_pk_mul_f32 v[192:193], v[192:193], v[200:201] op_sel_hi:[1,0]
	v_pk_mul_f32 v[196:197], v[196:197], v[200:201] op_sel_hi:[1,0]
	v_pk_mul_f32 v[184:185], v[184:185], v[182:183]
	v_pk_mul_f32 v[188:189], v[188:189], v[186:187]
	v_pk_mul_f32 v[192:193], v[192:193], v[190:191]
	v_pk_mul_f32 v[196:197], v[196:197], v[194:195]
	v_cvt_pk_bf16_f32 v50, v184, v185
	v_cvt_pk_bf16_f32 v51, v188, v189
	v_cvt_pk_bf16_f32 v52, v192, v193
	v_cvt_pk_bf16_f32 v53, v196, v197
	global_store_dwordx4 v[66:67], v[50:53], off
	s_nop 1
	v_add_u32_e32 v52, 0x90, v150
	v_ashrrev_i32_e32 v53, 31, v52
	v_mad_i64_i32 v[50:51], s[0:1], v52, s4, v[146:147]
	v_lshl_add_u64 v[52:53], v[52:53], 4, s[22:23]
	global_load_dwordx4 v[52:55], v[52:53], off
	v_lshl_add_u64 v[50:51], v[50:51], 0, v[148:149]
	s_waitcnt vmcnt(0)
	v_mov_b32_e32 v56, v53
	v_mov_b32_e32 v57, v54
	v_mov_b32_e32 v53, v55
	v_pk_add_f32 v[52:53], v[56:57], v[52:53]
	s_nop 0
	v_add_f32_e32 v52, v52, v53
	v_fmamk_f32 v52, v52, 0x3a800000, v138
	v_rsq_f32_e32 v52, v52
	s_nop 0
	v_mul_f32_e32 v198, 0xbfb8aa3b, v52
	v_mul_f32_e32 v200, v52, v52
	v_mov_b32_e32 v202, 1.0
	v_pk_mul_f32 v[182:183], v[46:47], v[198:199] op_sel_hi:[1,0]
	v_pk_mul_f32 v[186:187], v[48:49], v[198:199] op_sel_hi:[1,0]
	v_pk_mul_f32 v[190:191], v[42:43], v[198:199] op_sel_hi:[1,0]
	v_pk_mul_f32 v[194:195], v[44:45], v[198:199] op_sel_hi:[1,0]
	v_exp_f32_e32 v182, v182
	v_exp_f32_e32 v183, v183
	v_exp_f32_e32 v186, v186
	v_exp_f32_e32 v187, v187
	v_exp_f32_e32 v190, v190
	v_exp_f32_e32 v191, v191
	v_exp_f32_e32 v194, v194
	v_exp_f32_e32 v195, v195
	v_pk_mul_f32 v[184:185], v[46:47], v[38:39]
	v_pk_mul_f32 v[188:189], v[48:49], v[40:41]
	v_pk_mul_f32 v[192:193], v[42:43], v[34:35]
	v_pk_mul_f32 v[196:197], v[44:45], v[36:37]
	v_pk_add_f32 v[182:183], v[182:183], v[202:203] op_sel_hi:[1,0]
	v_pk_add_f32 v[186:187], v[186:187], v[202:203] op_sel_hi:[1,0]
	v_pk_add_f32 v[190:191], v[190:191], v[202:203] op_sel_hi:[1,0]
	v_pk_add_f32 v[194:195], v[194:195], v[202:203] op_sel_hi:[1,0]
	v_rcp_f32_e32 v182, v182
	v_rcp_f32_e32 v183, v183
	v_rcp_f32_e32 v186, v186
	v_rcp_f32_e32 v187, v187
	v_rcp_f32_e32 v190, v190
	v_rcp_f32_e32 v191, v191
	v_rcp_f32_e32 v194, v194
	v_rcp_f32_e32 v195, v195
	v_pk_mul_f32 v[184:185], v[184:185], v[200:201] op_sel_hi:[1,0]
	v_pk_mul_f32 v[188:189], v[188:189], v[200:201] op_sel_hi:[1,0]
	v_pk_mul_f32 v[192:193], v[192:193], v[200:201] op_sel_hi:[1,0]
	v_pk_mul_f32 v[196:197], v[196:197], v[200:201] op_sel_hi:[1,0]
	v_pk_mul_f32 v[184:185], v[184:185], v[182:183]
	v_pk_mul_f32 v[188:189], v[188:189], v[186:187]
	v_pk_mul_f32 v[192:193], v[192:193], v[190:191]
	v_pk_mul_f32 v[196:197], v[196:197], v[194:195]
	v_cvt_pk_bf16_f32 v34, v184, v185
	v_cvt_pk_bf16_f32 v35, v188, v189
	v_cvt_pk_bf16_f32 v36, v192, v193
	v_cvt_pk_bf16_f32 v37, v196, v197
	global_store_dwordx4 v[50:51], v[34:37], off
	s_nop 1
	v_add_u32_e32 v36, 0xa0, v150
	v_ashrrev_i32_e32 v37, 31, v36
	v_mad_i64_i32 v[34:35], s[0:1], v36, s4, v[146:147]
	v_lshl_add_u64 v[36:37], v[36:37], 4, s[22:23]
	global_load_dwordx4 v[36:39], v[36:37], off
	v_lshl_add_u64 v[34:35], v[34:35], 0, v[148:149]
	s_waitcnt vmcnt(0)
; __device__ __forceinline__ unsigned cvt_pk_bf16(float lo, float hi) { unsigned r; asm volatile("v_cvt_pk_bf16_f32 %0, %1, %2" : "=v"(r) : "v"(lo), "v"(hi)); return r; }
; __device__ __forceinline__ float silu_f(float g) { return g * __builtin_amdgcn_rcpf(1.0f + __expf(-g)); }
; __device__ __forceinline__ float row_rstd(const float* rss, int row) { if (!rss) return 1.0f; const f32x4 s = *(const f32x4*)(rss + 4 * (size_t)row); return __builtin_amdgcn_rsqf(((s[0] + s[1]) + (s[2] + s[3])) * (1.0f / 1024.0f) + 1e-6f); }
;     __device__ __forceinline__ void operator()(const f32x4 (&acc)[2][2][4][2], const Unit& u, int wr, int wc, int fr, int fq) const {
;     ...
;             for (int m = 0; m < 4; ++m) { const int row = row0 + ai * HALF + m * 16; bf16_t* rowp = O + (size_t)row * ldc + col0; const float rs = row_rstd(rss, row);
;                 const f32x4 g0 = acc[ai][0][m][0] * rs, g1 = acc[ai][0][m][1] * rs, u0 = acc[ai][1][m][0] * rs, u1 = acc[ai][1][m][1] * rs;
;                 u32x4 w;
;                 w.x = cvt_pk_bf16(silu_f(g0[0]) * u0[0], silu_f(g0[1]) * u0[1]); w.y = cvt_pk_bf16(silu_f(g0[2]) * u0[2], silu_f(g0[3]) * u0[3]);
;                 w.z = cvt_pk_bf16(silu_f(g1[0]) * u1[0], silu_f(g1[1]) * u1[1]); w.w = cvt_pk_bf16(silu_f(g1[2]) * u1[2], silu_f(g1[3]) * u1[3]);
;                 *(u32x4*)rowp = w; }
	v_mov_b32_e32 v40, v37
	v_mov_b32_e32 v41, v38
	v_mov_b32_e32 v37, v39
	v_pk_add_f32 v[36:37], v[40:41], v[36:37]
	s_nop 0
	v_add_f32_e32 v36, v36, v37
	v_fmamk_f32 v36, v36, 0x3a800000, v138
	v_rsq_f32_e32 v36, v36
	s_nop 0
	v_mul_f32_e32 v198, 0xbfb8aa3b, v36
	v_mul_f32_e32 v200, v36, v36
	v_mov_b32_e32 v202, 1.0
	v_pk_mul_f32 v[182:183], v[30:31], v[198:199] op_sel_hi:[1,0]
	v_pk_mul_f32 v[186:187], v[32:33], v[198:199] op_sel_hi:[1,0]
	v_pk_mul_f32 v[190:191], v[26:27], v[198:199] op_sel_hi:[1,0]
	v_pk_mul_f32 v[194:195], v[28:29], v[198:199] op_sel_hi:[1,0]
	v_exp_f32_e32 v182, v182
	v_exp_f32_e32 v183, v183
	v_exp_f32_e32 v186, v186
	v_exp_f32_e32 v187, v187
	v_exp_f32_e32 v190, v190
	v_exp_f32_e32 v191, v191
	v_exp_f32_e32 v194, v194
	v_exp_f32_e32 v195, v195
	v_pk_mul_f32 v[184:185], v[30:31], v[22:23]
	v_pk_mul_f32 v[188:189], v[32:33], v[24:25]
	v_pk_mul_f32 v[192:193], v[26:27], v[18:19]
	v_pk_mul_f32 v[196:197], v[28:29], v[20:21]
	v_pk_add_f32 v[182:183], v[182:183], v[202:203] op_sel_hi:[1,0]
	v_pk_add_f32 v[186:187], v[186:187], v[202:203] op_sel_hi:[1,0]
	v_pk_add_f32 v[190:191], v[190:191], v[202:203] op_sel_hi:[1,0]
	v_pk_add_f32 v[194:195], v[194:195], v[202:203] op_sel_hi:[1,0]
	v_rcp_f32_e32 v182, v182
	v_rcp_f32_e32 v183, v183
	v_rcp_f32_e32 v186, v186
	v_rcp_f32_e32 v187, v187
	v_rcp_f32_e32 v190, v190
	v_rcp_f32_e32 v191, v191
	v_rcp_f32_e32 v194, v194
	v_rcp_f32_e32 v195, v195
	v_pk_mul_f32 v[184:185], v[184:185], v[200:201] op_sel_hi:[1,0]
	v_pk_mul_f32 v[188:189], v[188:189], v[200:201] op_sel_hi:[1,0]
	v_pk_mul_f32 v[192:193], v[192:193], v[200:201] op_sel_hi:[1,0]
	v_pk_mul_f32 v[196:197], v[196:197], v[200:201] op_sel_hi:[1,0]
	v_pk_mul_f32 v[184:185], v[184:185], v[182:183]
	v_pk_mul_f32 v[188:189], v[188:189], v[186:187]
	v_pk_mul_f32 v[192:193], v[192:193], v[190:191]
	v_pk_mul_f32 v[196:197], v[196:197], v[194:195]
	v_cvt_pk_bf16_f32 v18, v184, v185
	v_cvt_pk_bf16_f32 v19, v188, v189
	v_cvt_pk_bf16_f32 v20, v192, v193
	v_cvt_pk_bf16_f32 v21, v196, v197
	global_store_dwordx4 v[34:35], v[18:21], off
	s_nop 1
	v_add_u32_e32 v18, 0xb0, v150
	v_ashrrev_i32_e32 v19, 31, v18
	v_lshl_add_u64 v[20:21], v[18:19], 4, s[22:23]
	global_load_dwordx4 v[20:23], v[20:21], off
	s_waitcnt vmcnt(0)
	v_mov_b32_e32 v24, v21
	v_mov_b32_e32 v25, v22
	v_mov_b32_e32 v21, v23
	v_pk_add_f32 v[20:21], v[24:25], v[20:21]
	s_nop 0
	v_add_f32_e32 v19, v20, v21
	v_fmamk_f32 v19, v19, 0x3a800000, v138
	v_rsq_f32_e32 v20, v19
	s_nop 0
	v_mad_i64_i32 v[18:19], s[0:1], v18, s4, v[146:147]
	v_lshl_add_u64 v[18:19], v[18:19], 0, v[148:149]
	v_mul_f32_e32 v198, 0xbfb8aa3b, v20
	v_mul_f32_e32 v200, v20, v20
	v_mov_b32_e32 v202, 1.0
	v_pk_mul_f32 v[182:183], v[14:15], v[198:199] op_sel_hi:[1,0]
	v_pk_mul_f32 v[186:187], v[16:17], v[198:199] op_sel_hi:[1,0]
	v_pk_mul_f32 v[190:191], v[10:11], v[198:199] op_sel_hi:[1,0]
	v_pk_mul_f32 v[194:195], v[12:13], v[198:199] op_sel_hi:[1,0]
	v_exp_f32_e32 v182, v182
	v_exp_f32_e32 v183, v183
	v_exp_f32_e32 v186, v186
	v_exp_f32_e32 v187, v187
	v_exp_f32_e32 v190, v190
	v_exp_f32_e32 v191, v191
	v_exp_f32_e32 v194, v194
	v_exp_f32_e32 v195, v195
	v_pk_mul_f32 v[184:185], v[14:15], v[6:7]
	v_pk_mul_f32 v[188:189], v[16:17], v[8:9]
	v_pk_mul_f32 v[192:193], v[10:11], v[2:3]
	v_pk_mul_f32 v[196:197], v[12:13], v[4:5]
	v_pk_add_f32 v[182:183], v[182:183], v[202:203] op_sel_hi:[1,0]
	v_pk_add_f32 v[186:187], v[186:187], v[202:203] op_sel_hi:[1,0]
	v_pk_add_f32 v[190:191], v[190:191], v[202:203] op_sel_hi:[1,0]
	v_pk_add_f32 v[194:195], v[194:195], v[202:203] op_sel_hi:[1,0]
	v_rcp_f32_e32 v182, v182
	v_rcp_f32_e32 v183, v183
	v_rcp_f32_e32 v186, v186
	v_rcp_f32_e32 v187, v187
	v_rcp_f32_e32 v190, v190
	v_rcp_f32_e32 v191, v191
	v_rcp_f32_e32 v194, v194
	v_rcp_f32_e32 v195, v195
	v_pk_mul_f32 v[184:185], v[184:185], v[200:201] op_sel_hi:[1,0]
	v_pk_mul_f32 v[188:189], v[188:189], v[200:201] op_sel_hi:[1,0]
	v_pk_mul_f32 v[192:193], v[192:193], v[200:201] op_sel_hi:[1,0]
	v_pk_mul_f32 v[196:197], v[196:197], v[200:201] op_sel_hi:[1,0]
	v_pk_mul_f32 v[184:185], v[184:185], v[182:183]
	v_pk_mul_f32 v[188:189], v[188:189], v[186:187]
	v_pk_mul_f32 v[192:193], v[192:193], v[190:191]
	v_pk_mul_f32 v[196:197], v[196:197], v[194:195]
	v_cvt_pk_bf16_f32 v2, v184, v185
	v_cvt_pk_bf16_f32 v3, v188, v189
	v_cvt_pk_bf16_f32 v4, v192, v193
	v_cvt_pk_bf16_f32 v5, v196, v197
	global_store_dwordx4 v[18:19], v[2:5], off
	s_cbranch_vccnz .LBB0_199
	s_andn2_b64 vcc, exec, s[18:19]
	s_cbranch_vccnz .LBB0_198
	s_barrier
	s_branch .LBB0_198

; __device__ __forceinline__ unsigned cvt_pk_bf16(float lo, float hi) { unsigned r; asm volatile("v_cvt_pk_bf16_f32 %0, %1, %2" : "=v"(r) : "v"(lo), "v"(hi)); return r; }
; __device__ __forceinline__ float silu_f(float g) { return g * __builtin_amdgcn_rcpf(1.0f + __expf(-g)); }
; __device__ __forceinline__ float row_rstd(const float* rss, int row) { if (!rss) return 1.0f; const f32x4 s = *(const f32x4*)(rss + 4 * (size_t)row); return __builtin_amdgcn_rsqf(((s[0] + s[1]) + (s[2] + s[3])) * (1.0f / 1024.0f) + 1e-6f); }
;     __device__ __forceinline__ void operator()(const f32x4 (&acc)[2][2][4][2], const Unit& u, int wr, int wc, int fr, int fq) const {
;     ...
;             for (int m = 0; m < 4; ++m) { const int row = row0 + ai * HALF + m * 16; bf16_t* rowp = O + (size_t)row * ldc + col0; const float rs = row_rstd(rss, row);
;                 const f32x4 g0 = acc[ai][0][m][0] * rs, g1 = acc[ai][0][m][1] * rs, u0 = acc[ai][1][m][0] * rs, u1 = acc[ai][1][m][1] * rs;
;                 u32x4 w;
;                 w.x = cvt_pk_bf16(silu_f(g0[0]) * u0[0], silu_f(g0[1]) * u0[1]); w.y = cvt_pk_bf16(silu_f(g0[2]) * u0[2], silu_f(g0[3]) * u0[3]);
;                 w.z = cvt_pk_bf16(silu_f(g1[0]) * u1[0], silu_f(g1[1]) * u1[1]); w.w = cvt_pk_bf16(silu_f(g1[2]) * u1[2], silu_f(g1[3]) * u1[3]);
;                 *(u32x4*)rowp = w; }
.LBB0_1133:
	v_lshl_or_b32 v146, s0, 7, v151
	v_lshl_add_u32 v148, s1, 8, v1
	v_ashrrev_i32_e32 v147, 31, v146
	v_mov_b64_e32 v[144:145], s[22:23]
	v_ashrrev_i32_e32 v149, 31, v148
	v_mad_i64_i32 v[160:161], s[0:1], v148, s4, v[144:145]
	v_lshlrev_b64 v[146:147], 1, v[146:147]
	v_lshl_add_u64 v[164:165], v[160:161], 0, v[146:147]
	v_lshl_add_u64 v[160:161], v[148:149], 4, s[24:25]
	global_load_dwordx4 v[160:163], v[160:161], off
	s_mov_b64 s[34:35], -1
	s_and_b64 vcc, exec, s[8:9]
	s_waitcnt vmcnt(0)
	v_mov_b32_e32 v166, v161
	v_mov_b32_e32 v167, v162
	v_mov_b32_e32 v161, v163
	v_pk_add_f32 v[160:161], v[166:167], v[160:161]
	s_nop 0
	v_add_f32_e32 v149, v160, v161
	v_fmamk_f32 v149, v149, 0x3a800000, v138
	v_rsq_f32_e32 v160, v149
	s_nop 0
	v_mul_f32_e32 v198, 0xbfb8aa3b, v160
	v_mul_f32_e32 v200, v160, v160
	v_mov_b32_e32 v202, 1.0
	v_pk_mul_f32 v[182:183], v[122:123], v[198:199] op_sel_hi:[1,0]
	v_pk_mul_f32 v[186:187], v[124:125], v[198:199] op_sel_hi:[1,0]
	v_pk_mul_f32 v[190:191], v[126:127], v[198:199] op_sel_hi:[1,0]
	v_pk_mul_f32 v[194:195], v[128:129], v[198:199] op_sel_hi:[1,0]
	v_exp_f32_e32 v182, v182
	v_exp_f32_e32 v183, v183
	v_exp_f32_e32 v186, v186
	v_exp_f32_e32 v187, v187
	v_exp_f32_e32 v190, v190
	v_exp_f32_e32 v191, v191
	v_exp_f32_e32 v194, v194
	v_exp_f32_e32 v195, v195
	v_pk_mul_f32 v[184:185], v[122:123], v[118:119]
	v_pk_mul_f32 v[188:189], v[124:125], v[120:121]
	v_pk_mul_f32 v[192:193], v[126:127], v[114:115]
	v_pk_mul_f32 v[196:197], v[128:129], v[116:117]
	v_pk_add_f32 v[182:183], v[182:183], v[202:203] op_sel_hi:[1,0]
	v_pk_add_f32 v[186:187], v[186:187], v[202:203] op_sel_hi:[1,0]
	v_pk_add_f32 v[190:191], v[190:191], v[202:203] op_sel_hi:[1,0]
	v_pk_add_f32 v[194:195], v[194:195], v[202:203] op_sel_hi:[1,0]
	v_rcp_f32_e32 v182, v182
	v_rcp_f32_e32 v183, v183
	v_rcp_f32_e32 v186, v186
	v_rcp_f32_e32 v187, v187
	v_rcp_f32_e32 v190, v190
	v_rcp_f32_e32 v191, v191
	v_rcp_f32_e32 v194, v194
	v_rcp_f32_e32 v195, v195
	v_pk_mul_f32 v[184:185], v[184:185], v[200:201] op_sel_hi:[1,0]
	v_pk_mul_f32 v[188:189], v[188:189], v[200:201] op_sel_hi:[1,0]
	v_pk_mul_f32 v[192:193], v[192:193], v[200:201] op_sel_hi:[1,0]
	v_pk_mul_f32 v[196:197], v[196:197], v[200:201] op_sel_hi:[1,0]
	v_pk_mul_f32 v[184:185], v[184:185], v[182:183]
	v_pk_mul_f32 v[188:189], v[188:189], v[186:187]
	v_pk_mul_f32 v[192:193], v[192:193], v[190:191]
	v_pk_mul_f32 v[196:197], v[196:197], v[194:195]
	v_cvt_pk_bf16_f32 v114, v184, v185
	v_cvt_pk_bf16_f32 v115, v188, v189
	v_cvt_pk_bf16_f32 v116, v192, v193
	v_cvt_pk_bf16_f32 v117, v196, v197
	global_store_dwordx4 v[164:165], v[114:117], off
	s_nop 1
	v_or_b32_e32 v116, 16, v148
	v_ashrrev_i32_e32 v117, 31, v116
	v_mad_i64_i32 v[114:115], s[0:1], v116, s4, v[144:145]
	v_lshl_add_u64 v[116:117], v[116:117], 4, s[24:25]
	global_load_dwordx4 v[116:119], v[116:117], off
	v_lshl_add_u64 v[114:115], v[114:115], 0, v[146:147]
	s_waitcnt vmcnt(0)
	v_mov_b32_e32 v120, v117
	v_mov_b32_e32 v121, v118
	v_mov_b32_e32 v117, v119
	v_pk_add_f32 v[116:117], v[120:121], v[116:117]
	s_nop 0
	v_add_f32_e32 v116, v116, v117
	v_fmamk_f32 v116, v116, 0x3a800000, v138
	v_rsq_f32_e32 v116, v116
	s_nop 0
	v_mul_f32_e32 v198, 0xbfb8aa3b, v116
	v_mul_f32_e32 v200, v116, v116
	v_mov_b32_e32 v202, 1.0
	v_pk_mul_f32 v[182:183], v[110:111], v[198:199] op_sel_hi:[1,0]
	v_pk_mul_f32 v[186:187], v[112:113], v[198:199] op_sel_hi:[1,0]
	v_pk_mul_f32 v[190:191], v[106:107], v[198:199] op_sel_hi:[1,0]
	v_pk_mul_f32 v[194:195], v[108:109], v[198:199] op_sel_hi:[1,0]
	v_exp_f32_e32 v182, v182
	v_exp_f32_e32 v183, v183
	v_exp_f32_e32 v186, v186
	v_exp_f32_e32 v187, v187
	v_exp_f32_e32 v190, v190
	v_exp_f32_e32 v191, v191
	v_exp_f32_e32 v194, v194
	v_exp_f32_e32 v195, v195
	v_pk_mul_f32 v[184:185], v[110:111], v[102:103]
	v_pk_mul_f32 v[188:189], v[112:113], v[104:105]
	v_pk_mul_f32 v[192:193], v[106:107], v[98:99]
	v_pk_mul_f32 v[196:197], v[108:109], v[100:101]
	v_pk_add_f32 v[182:183], v[182:183], v[202:203] op_sel_hi:[1,0]
	v_pk_add_f32 v[186:187], v[186:187], v[202:203] op_sel_hi:[1,0]
	v_pk_add_f32 v[190:191], v[190:191], v[202:203] op_sel_hi:[1,0]
	v_pk_add_f32 v[194:195], v[194:195], v[202:203] op_sel_hi:[1,0]
	v_rcp_f32_e32 v182, v182
	v_rcp_f32_e32 v183, v183
	v_rcp_f32_e32 v186, v186
	v_rcp_f32_e32 v187, v187
	v_rcp_f32_e32 v190, v190
	v_rcp_f32_e32 v191, v191
	v_rcp_f32_e32 v194, v194
	v_rcp_f32_e32 v195, v195
	v_pk_mul_f32 v[184:185], v[184:185], v[200:201] op_sel_hi:[1,0]
	v_pk_mul_f32 v[188:189], v[188:189], v[200:201] op_sel_hi:[1,0]
	v_pk_mul_f32 v[192:193], v[192:193], v[200:201] op_sel_hi:[1,0]
	v_pk_mul_f32 v[196:197], v[196:197], v[200:201] op_sel_hi:[1,0]
	v_pk_mul_f32 v[184:185], v[184:185], v[182:183]
	v_pk_mul_f32 v[188:189], v[188:189], v[186:187]
	v_pk_mul_f32 v[192:193], v[192:193], v[190:191]
	v_pk_mul_f32 v[196:197], v[196:197], v[194:195]
	v_cvt_pk_bf16_f32 v98, v184, v185
	v_cvt_pk_bf16_f32 v99, v188, v189
	v_cvt_pk_bf16_f32 v100, v192, v193
	v_cvt_pk_bf16_f32 v101, v196, v197
	global_store_dwordx4 v[114:115], v[98:101], off
	s_nop 1
	v_or_b32_e32 v100, 32, v148
	v_ashrrev_i32_e32 v101, 31, v100
	v_mad_i64_i32 v[98:99], s[0:1], v100, s4, v[144:145]
	v_lshl_add_u64 v[100:101], v[100:101], 4, s[24:25]
	global_load_dwordx4 v[100:103], v[100:101], off
	v_lshl_add_u64 v[98:99], v[98:99], 0, v[146:147]
	s_waitcnt vmcnt(0)
; __device__ __forceinline__ unsigned cvt_pk_bf16(float lo, float hi) { unsigned r; asm volatile("v_cvt_pk_bf16_f32 %0, %1, %2" : "=v"(r) : "v"(lo), "v"(hi)); return r; }
; __device__ __forceinline__ float silu_f(float g) { return g * __builtin_amdgcn_rcpf(1.0f + __expf(-g)); }
; __device__ __forceinline__ float row_rstd(const float* rss, int row) { if (!rss) return 1.0f; const f32x4 s = *(const f32x4*)(rss + 4 * (size_t)row); return __builtin_amdgcn_rsqf(((s[0] + s[1]) + (s[2] + s[3])) * (1.0f / 1024.0f) + 1e-6f); }
;     __device__ __forceinline__ void operator()(const f32x4 (&acc)[2][2][4][2], const Unit& u, int wr, int wc, int fr, int fq) const {
;     ...
;             for (int m = 0; m < 4; ++m) { const int row = row0 + ai * HALF + m * 16; bf16_t* rowp = O + (size_t)row * ldc + col0; const float rs = row_rstd(rss, row);
;                 const f32x4 g0 = acc[ai][0][m][0] * rs, g1 = acc[ai][0][m][1] * rs, u0 = acc[ai][1][m][0] * rs, u1 = acc[ai][1][m][1] * rs;
;                 u32x4 w;
;                 w.x = cvt_pk_bf16(silu_f(g0[0]) * u0[0], silu_f(g0[1]) * u0[1]); w.y = cvt_pk_bf16(silu_f(g0[2]) * u0[2], silu_f(g0[3]) * u0[3]);
;                 w.z = cvt_pk_bf16(silu_f(g1[0]) * u1[0], silu_f(g1[1]) * u1[1]); w.w = cvt_pk_bf16(silu_f(g1[2]) * u1[2], silu_f(g1[3]) * u1[3]);
;                 *(u32x4*)rowp = w; }
	v_mov_b32_e32 v104, v101
	v_mov_b32_e32 v105, v102
	v_mov_b32_e32 v101, v103
	v_pk_add_f32 v[100:101], v[104:105], v[100:101]
	s_nop 0
	v_add_f32_e32 v100, v100, v101
	v_fmamk_f32 v100, v100, 0x3a800000, v138
	v_rsq_f32_e32 v100, v100
	s_nop 0
	v_mul_f32_e32 v198, 0xbfb8aa3b, v100
	v_mul_f32_e32 v200, v100, v100
	v_mov_b32_e32 v202, 1.0
	v_pk_mul_f32 v[182:183], v[94:95], v[198:199] op_sel_hi:[1,0]
	v_pk_mul_f32 v[186:187], v[96:97], v[198:199] op_sel_hi:[1,0]
	v_pk_mul_f32 v[190:191], v[90:91], v[198:199] op_sel_hi:[1,0]
	v_pk_mul_f32 v[194:195], v[92:93], v[198:199] op_sel_hi:[1,0]
	v_exp_f32_e32 v182, v182
	v_exp_f32_e32 v183, v183
	v_exp_f32_e32 v186, v186
	v_exp_f32_e32 v187, v187
	v_exp_f32_e32 v190, v190
	v_exp_f32_e32 v191, v191
	v_exp_f32_e32 v194, v194
	v_exp_f32_e32 v195, v195
	v_pk_mul_f32 v[184:185], v[94:95], v[86:87]
	v_pk_mul_f32 v[188:189], v[96:97], v[88:89]
	v_pk_mul_f32 v[192:193], v[90:91], v[82:83]
	v_pk_mul_f32 v[196:197], v[92:93], v[84:85]
	v_pk_add_f32 v[182:183], v[182:183], v[202:203] op_sel_hi:[1,0]
	v_pk_add_f32 v[186:187], v[186:187], v[202:203] op_sel_hi:[1,0]
	v_pk_add_f32 v[190:191], v[190:191], v[202:203] op_sel_hi:[1,0]
	v_pk_add_f32 v[194:195], v[194:195], v[202:203] op_sel_hi:[1,0]
	v_rcp_f32_e32 v182, v182
	v_rcp_f32_e32 v183, v183
	v_rcp_f32_e32 v186, v186
	v_rcp_f32_e32 v187, v187
	v_rcp_f32_e32 v190, v190
	v_rcp_f32_e32 v191, v191
	v_rcp_f32_e32 v194, v194
	v_rcp_f32_e32 v195, v195
	v_pk_mul_f32 v[184:185], v[184:185], v[200:201] op_sel_hi:[1,0]
	v_pk_mul_f32 v[188:189], v[188:189], v[200:201] op_sel_hi:[1,0]
	v_pk_mul_f32 v[192:193], v[192:193], v[200:201] op_sel_hi:[1,0]
	v_pk_mul_f32 v[196:197], v[196:197], v[200:201] op_sel_hi:[1,0]
	v_pk_mul_f32 v[184:185], v[184:185], v[182:183]
	v_pk_mul_f32 v[188:189], v[188:189], v[186:187]
	v_pk_mul_f32 v[192:193], v[192:193], v[190:191]
	v_pk_mul_f32 v[196:197], v[196:197], v[194:195]
	v_cvt_pk_bf16_f32 v82, v184, v185
	v_cvt_pk_bf16_f32 v83, v188, v189
	v_cvt_pk_bf16_f32 v84, v192, v193
	v_cvt_pk_bf16_f32 v85, v196, v197
	global_store_dwordx4 v[98:99], v[82:85], off
	s_nop 1
	v_or_b32_e32 v84, 48, v148
	v_ashrrev_i32_e32 v85, 31, v84
	v_mad_i64_i32 v[82:83], s[0:1], v84, s4, v[144:145]
	v_lshl_add_u64 v[84:85], v[84:85], 4, s[24:25]
	global_load_dwordx4 v[84:87], v[84:85], off
	v_lshl_add_u64 v[82:83], v[82:83], 0, v[146:147]
	s_waitcnt vmcnt(0)
	v_mov_b32_e32 v88, v85
	v_mov_b32_e32 v89, v86
	v_mov_b32_e32 v85, v87
	v_pk_add_f32 v[84:85], v[88:89], v[84:85]
	s_nop 0
	v_add_f32_e32 v84, v84, v85
	v_fmamk_f32 v84, v84, 0x3a800000, v138
	v_rsq_f32_e32 v84, v84
	s_nop 0
	v_mul_f32_e32 v198, 0xbfb8aa3b, v84
	v_mul_f32_e32 v200, v84, v84
	v_mov_b32_e32 v202, 1.0
	v_pk_mul_f32 v[182:183], v[78:79], v[198:199] op_sel_hi:[1,0]
	v_pk_mul_f32 v[186:187], v[80:81], v[198:199] op_sel_hi:[1,0]
	v_pk_mul_f32 v[190:191], v[74:75], v[198:199] op_sel_hi:[1,0]
	v_pk_mul_f32 v[194:195], v[76:77], v[198:199] op_sel_hi:[1,0]
	v_exp_f32_e32 v182, v182
	v_exp_f32_e32 v183, v183
	v_exp_f32_e32 v186, v186
	v_exp_f32_e32 v187, v187
	v_exp_f32_e32 v190, v190
	v_exp_f32_e32 v191, v191
	v_exp_f32_e32 v194, v194
	v_exp_f32_e32 v195, v195
	v_pk_mul_f32 v[184:185], v[78:79], v[70:71]
	v_pk_mul_f32 v[188:189], v[80:81], v[72:73]
	v_pk_mul_f32 v[192:193], v[74:75], v[66:67]
	v_pk_mul_f32 v[196:197], v[76:77], v[68:69]
	v_pk_add_f32 v[182:183], v[182:183], v[202:203] op_sel_hi:[1,0]
	v_pk_add_f32 v[186:187], v[186:187], v[202:203] op_sel_hi:[1,0]
	v_pk_add_f32 v[190:191], v[190:191], v[202:203] op_sel_hi:[1,0]
	v_pk_add_f32 v[194:195], v[194:195], v[202:203] op_sel_hi:[1,0]
	v_rcp_f32_e32 v182, v182
	v_rcp_f32_e32 v183, v183
	v_rcp_f32_e32 v186, v186
	v_rcp_f32_e32 v187, v187
	v_rcp_f32_e32 v190, v190
	v_rcp_f32_e32 v191, v191
	v_rcp_f32_e32 v194, v194
	v_rcp_f32_e32 v195, v195
	v_pk_mul_f32 v[184:185], v[184:185], v[200:201] op_sel_hi:[1,0]
	v_pk_mul_f32 v[188:189], v[188:189], v[200:201] op_sel_hi:[1,0]
	v_pk_mul_f32 v[192:193], v[192:193], v[200:201] op_sel_hi:[1,0]
	v_pk_mul_f32 v[196:197], v[196:197], v[200:201] op_sel_hi:[1,0]
	v_pk_mul_f32 v[184:185], v[184:185], v[182:183]
	v_pk_mul_f32 v[188:189], v[188:189], v[186:187]
	v_pk_mul_f32 v[192:193], v[192:193], v[190:191]
	v_pk_mul_f32 v[196:197], v[196:197], v[194:195]
	v_cvt_pk_bf16_f32 v66, v184, v185
	v_cvt_pk_bf16_f32 v67, v188, v189
	v_cvt_pk_bf16_f32 v68, v192, v193
	v_cvt_pk_bf16_f32 v69, v196, v197
	global_store_dwordx4 v[82:83], v[66:69], off
	s_nop 1
	v_add_u32_e32 v68, 0x80, v148
	v_ashrrev_i32_e32 v69, 31, v68
	v_mad_i64_i32 v[66:67], s[0:1], v68, s4, v[144:145]
	v_lshl_add_u64 v[68:69], v[68:69], 4, s[24:25]
	global_load_dwordx4 v[68:71], v[68:69], off
	v_lshl_add_u64 v[66:67], v[66:67], 0, v[146:147]
	s_waitcnt vmcnt(0)
; __device__ __forceinline__ unsigned cvt_pk_bf16(float lo, float hi) { unsigned r; asm volatile("v_cvt_pk_bf16_f32 %0, %1, %2" : "=v"(r) : "v"(lo), "v"(hi)); return r; }
; __device__ __forceinline__ float silu_f(float g) { return g * __builtin_amdgcn_rcpf(1.0f + __expf(-g)); }
; __device__ __forceinline__ float row_rstd(const float* rss, int row) { if (!rss) return 1.0f; const f32x4 s = *(const f32x4*)(rss + 4 * (size_t)row); return __builtin_amdgcn_rsqf(((s[0] + s[1]) + (s[2] + s[3])) * (1.0f / 1024.0f) + 1e-6f); }
;     __device__ __forceinline__ void operator()(const f32x4 (&acc)[2][2][4][2], const Unit& u, int wr, int wc, int fr, int fq) const {
;     ...
;             for (int m = 0; m < 4; ++m) { const int row = row0 + ai * HALF + m * 16; bf16_t* rowp = O + (size_t)row * ldc + col0; const float rs = row_rstd(rss, row);
;                 const f32x4 g0 = acc[ai][0][m][0] * rs, g1 = acc[ai][0][m][1] * rs, u0 = acc[ai][1][m][0] * rs, u1 = acc[ai][1][m][1] * rs;
;                 u32x4 w;
;                 w.x = cvt_pk_bf16(silu_f(g0[0]) * u0[0], silu_f(g0[1]) * u0[1]); w.y = cvt_pk_bf16(silu_f(g0[2]) * u0[2], silu_f(g0[3]) * u0[3]);
;                 w.z = cvt_pk_bf16(silu_f(g1[0]) * u1[0], silu_f(g1[1]) * u1[1]); w.w = cvt_pk_bf16(silu_f(g1[2]) * u1[2], silu_f(g1[3]) * u1[3]);
;                 *(u32x4*)rowp = w; }
	v_mov_b32_e32 v72, v69
	v_mov_b32_e32 v73, v70
	v_mov_b32_e32 v69, v71
	v_pk_add_f32 v[68:69], v[72:73], v[68:69]
	s_nop 0
	v_add_f32_e32 v68, v68, v69
	v_fmamk_f32 v68, v68, 0x3a800000, v138
	v_rsq_f32_e32 v68, v68
	s_nop 0
	v_mul_f32_e32 v198, 0xbfb8aa3b, v68
	v_mul_f32_e32 v200, v68, v68
	v_mov_b32_e32 v202, 1.0
	v_pk_mul_f32 v[182:183], v[62:63], v[198:199] op_sel_hi:[1,0]
	v_pk_mul_f32 v[186:187], v[64:65], v[198:199] op_sel_hi:[1,0]
	v_pk_mul_f32 v[190:191], v[58:59], v[198:199] op_sel_hi:[1,0]
	v_pk_mul_f32 v[194:195], v[60:61], v[198:199] op_sel_hi:[1,0]
	v_exp_f32_e32 v182, v182
	v_exp_f32_e32 v183, v183
	v_exp_f32_e32 v186, v186
	v_exp_f32_e32 v187, v187
	v_exp_f32_e32 v190, v190
	v_exp_f32_e32 v191, v191
	v_exp_f32_e32 v194, v194
	v_exp_f32_e32 v195, v195
	v_pk_mul_f32 v[184:185], v[62:63], v[54:55]
	v_pk_mul_f32 v[188:189], v[64:65], v[56:57]
	v_pk_mul_f32 v[192:193], v[58:59], v[50:51]
	v_pk_mul_f32 v[196:197], v[60:61], v[52:53]
	v_pk_add_f32 v[182:183], v[182:183], v[202:203] op_sel_hi:[1,0]
	v_pk_add_f32 v[186:187], v[186:187], v[202:203] op_sel_hi:[1,0]
	v_pk_add_f32 v[190:191], v[190:191], v[202:203] op_sel_hi:[1,0]
	v_pk_add_f32 v[194:195], v[194:195], v[202:203] op_sel_hi:[1,0]
	v_rcp_f32_e32 v182, v182
	v_rcp_f32_e32 v183, v183
	v_rcp_f32_e32 v186, v186
	v_rcp_f32_e32 v187, v187
	v_rcp_f32_e32 v190, v190
	v_rcp_f32_e32 v191, v191
	v_rcp_f32_e32 v194, v194
	v_rcp_f32_e32 v195, v195
	v_pk_mul_f32 v[184:185], v[184:185], v[200:201] op_sel_hi:[1,0]
	v_pk_mul_f32 v[188:189], v[188:189], v[200:201] op_sel_hi:[1,0]
	v_pk_mul_f32 v[192:193], v[192:193], v[200:201] op_sel_hi:[1,0]
	v_pk_mul_f32 v[196:197], v[196:197], v[200:201] op_sel_hi:[1,0]
	v_pk_mul_f32 v[184:185], v[184:185], v[182:183]
	v_pk_mul_f32 v[188:189], v[188:189], v[186:187]
	v_pk_mul_f32 v[192:193], v[192:193], v[190:191]
	v_pk_mul_f32 v[196:197], v[196:197], v[194:195]
	v_cvt_pk_bf16_f32 v50, v184, v185
	v_cvt_pk_bf16_f32 v51, v188, v189
	v_cvt_pk_bf16_f32 v52, v192, v193
	v_cvt_pk_bf16_f32 v53, v196, v197
	global_store_dwordx4 v[66:67], v[50:53], off
	s_nop 1
	v_add_u32_e32 v52, 0x90, v148
	v_ashrrev_i32_e32 v53, 31, v52
	v_mad_i64_i32 v[50:51], s[0:1], v52, s4, v[144:145]
	v_lshl_add_u64 v[52:53], v[52:53], 4, s[24:25]
	global_load_dwordx4 v[52:55], v[52:53], off
	v_lshl_add_u64 v[50:51], v[50:51], 0, v[146:147]
	s_waitcnt vmcnt(0)
	v_mov_b32_e32 v56, v53
	v_mov_b32_e32 v57, v54
	v_mov_b32_e32 v53, v55
	v_pk_add_f32 v[52:53], v[56:57], v[52:53]
	s_nop 0
	v_add_f32_e32 v52, v52, v53
	v_fmamk_f32 v52, v52, 0x3a800000, v138
	v_rsq_f32_e32 v52, v52
	s_nop 0
	v_mul_f32_e32 v198, 0xbfb8aa3b, v52
	v_mul_f32_e32 v200, v52, v52
	v_mov_b32_e32 v202, 1.0
	v_pk_mul_f32 v[182:183], v[46:47], v[198:199] op_sel_hi:[1,0]
	v_pk_mul_f32 v[186:187], v[48:49], v[198:199] op_sel_hi:[1,0]
	v_pk_mul_f32 v[190:191], v[42:43], v[198:199] op_sel_hi:[1,0]
	v_pk_mul_f32 v[194:195], v[44:45], v[198:199] op_sel_hi:[1,0]
	v_exp_f32_e32 v182, v182
	v_exp_f32_e32 v183, v183
	v_exp_f32_e32 v186, v186
	v_exp_f32_e32 v187, v187
	v_exp_f32_e32 v190, v190
	v_exp_f32_e32 v191, v191
	v_exp_f32_e32 v194, v194
	v_exp_f32_e32 v195, v195
	v_pk_mul_f32 v[184:185], v[46:47], v[38:39]
	v_pk_mul_f32 v[188:189], v[48:49], v[40:41]
	v_pk_mul_f32 v[192:193], v[42:43], v[34:35]
	v_pk_mul_f32 v[196:197], v[44:45], v[36:37]
	v_pk_add_f32 v[182:183], v[182:183], v[202:203] op_sel_hi:[1,0]
	v_pk_add_f32 v[186:187], v[186:187], v[202:203] op_sel_hi:[1,0]
	v_pk_add_f32 v[190:191], v[190:191], v[202:203] op_sel_hi:[1,0]
	v_pk_add_f32 v[194:195], v[194:195], v[202:203] op_sel_hi:[1,0]
	v_rcp_f32_e32 v182, v182
	v_rcp_f32_e32 v183, v183
	v_rcp_f32_e32 v186, v186
	v_rcp_f32_e32 v187, v187
	v_rcp_f32_e32 v190, v190
	v_rcp_f32_e32 v191, v191
	v_rcp_f32_e32 v194, v194
	v_rcp_f32_e32 v195, v195
	v_pk_mul_f32 v[184:185], v[184:185], v[200:201] op_sel_hi:[1,0]
	v_pk_mul_f32 v[188:189], v[188:189], v[200:201] op_sel_hi:[1,0]
	v_pk_mul_f32 v[192:193], v[192:193], v[200:201] op_sel_hi:[1,0]
	v_pk_mul_f32 v[196:197], v[196:197], v[200:201] op_sel_hi:[1,0]
	v_pk_mul_f32 v[184:185], v[184:185], v[182:183]
	v_pk_mul_f32 v[188:189], v[188:189], v[186:187]
	v_pk_mul_f32 v[192:193], v[192:193], v[190:191]
	v_pk_mul_f32 v[196:197], v[196:197], v[194:195]
	v_cvt_pk_bf16_f32 v34, v184, v185
	v_cvt_pk_bf16_f32 v35, v188, v189
	v_cvt_pk_bf16_f32 v36, v192, v193
	v_cvt_pk_bf16_f32 v37, v196, v197
	global_store_dwordx4 v[50:51], v[34:37], off
	s_nop 1
	v_add_u32_e32 v36, 0xa0, v148
	v_ashrrev_i32_e32 v37, 31, v36
	v_mad_i64_i32 v[34:35], s[0:1], v36, s4, v[144:145]
	v_lshl_add_u64 v[36:37], v[36:37], 4, s[24:25]
	global_load_dwordx4 v[36:39], v[36:37], off
	v_lshl_add_u64 v[34:35], v[34:35], 0, v[146:147]
	s_waitcnt vmcnt(0)
; __device__ __forceinline__ unsigned cvt_pk_bf16(float lo, float hi) { unsigned r; asm volatile("v_cvt_pk_bf16_f32 %0, %1, %2" : "=v"(r) : "v"(lo), "v"(hi)); return r; }
; __device__ __forceinline__ float silu_f(float g) { return g * __builtin_amdgcn_rcpf(1.0f + __expf(-g)); }
; __device__ __forceinline__ float row_rstd(const float* rss, int row) { if (!rss) return 1.0f; const f32x4 s = *(const f32x4*)(rss + 4 * (size_t)row); return __builtin_amdgcn_rsqf(((s[0] + s[1]) + (s[2] + s[3])) * (1.0f / 1024.0f) + 1e-6f); }
;     __device__ __forceinline__ void operator()(const f32x4 (&acc)[2][2][4][2], const Unit& u, int wr, int wc, int fr, int fq) const {
;     ...
;             for (int m = 0; m < 4; ++m) { const int row = row0 + ai * HALF + m * 16; bf16_t* rowp = O + (size_t)row * ldc + col0; const float rs = row_rstd(rss, row);
;                 const f32x4 g0 = acc[ai][0][m][0] * rs, g1 = acc[ai][0][m][1] * rs, u0 = acc[ai][1][m][0] * rs, u1 = acc[ai][1][m][1] * rs;
;                 u32x4 w;
;                 w.x = cvt_pk_bf16(silu_f(g0[0]) * u0[0], silu_f(g0[1]) * u0[1]); w.y = cvt_pk_bf16(silu_f(g0[2]) * u0[2], silu_f(g0[3]) * u0[3]);
;                 w.z = cvt_pk_bf16(silu_f(g1[0]) * u1[0], silu_f(g1[1]) * u1[1]); w.w = cvt_pk_bf16(silu_f(g1[2]) * u1[2], silu_f(g1[3]) * u1[3]);
;                 *(u32x4*)rowp = w; }
	v_mov_b32_e32 v40, v37
	v_mov_b32_e32 v41, v38
	v_mov_b32_e32 v37, v39
	v_pk_add_f32 v[36:37], v[40:41], v[36:37]
	s_nop 0
	v_add_f32_e32 v36, v36, v37
	v_fmamk_f32 v36, v36, 0x3a800000, v138
	v_rsq_f32_e32 v36, v36
	s_nop 0
	v_mul_f32_e32 v198, 0xbfb8aa3b, v36
	v_mul_f32_e32 v200, v36, v36
	v_mov_b32_e32 v202, 1.0
	v_pk_mul_f32 v[182:183], v[30:31], v[198:199] op_sel_hi:[1,0]
	v_pk_mul_f32 v[186:187], v[32:33], v[198:199] op_sel_hi:[1,0]
	v_pk_mul_f32 v[190:191], v[26:27], v[198:199] op_sel_hi:[1,0]
	v_pk_mul_f32 v[194:195], v[28:29], v[198:199] op_sel_hi:[1,0]
	v_exp_f32_e32 v182, v182
	v_exp_f32_e32 v183, v183
	v_exp_f32_e32 v186, v186
	v_exp_f32_e32 v187, v187
	v_exp_f32_e32 v190, v190
	v_exp_f32_e32 v191, v191
	v_exp_f32_e32 v194, v194
	v_exp_f32_e32 v195, v195
	v_pk_mul_f32 v[184:185], v[30:31], v[22:23]
	v_pk_mul_f32 v[188:189], v[32:33], v[24:25]
	v_pk_mul_f32 v[192:193], v[26:27], v[18:19]
	v_pk_mul_f32 v[196:197], v[28:29], v[20:21]
	v_pk_add_f32 v[182:183], v[182:183], v[202:203] op_sel_hi:[1,0]
	v_pk_add_f32 v[186:187], v[186:187], v[202:203] op_sel_hi:[1,0]
	v_pk_add_f32 v[190:191], v[190:191], v[202:203] op_sel_hi:[1,0]
	v_pk_add_f32 v[194:195], v[194:195], v[202:203] op_sel_hi:[1,0]
	v_rcp_f32_e32 v182, v182
	v_rcp_f32_e32 v183, v183
	v_rcp_f32_e32 v186, v186
	v_rcp_f32_e32 v187, v187
	v_rcp_f32_e32 v190, v190
	v_rcp_f32_e32 v191, v191
	v_rcp_f32_e32 v194, v194
	v_rcp_f32_e32 v195, v195
	v_pk_mul_f32 v[184:185], v[184:185], v[200:201] op_sel_hi:[1,0]
	v_pk_mul_f32 v[188:189], v[188:189], v[200:201] op_sel_hi:[1,0]
	v_pk_mul_f32 v[192:193], v[192:193], v[200:201] op_sel_hi:[1,0]
	v_pk_mul_f32 v[196:197], v[196:197], v[200:201] op_sel_hi:[1,0]
	v_pk_mul_f32 v[184:185], v[184:185], v[182:183]
	v_pk_mul_f32 v[188:189], v[188:189], v[186:187]
	v_pk_mul_f32 v[192:193], v[192:193], v[190:191]
	v_pk_mul_f32 v[196:197], v[196:197], v[194:195]
	v_cvt_pk_bf16_f32 v18, v184, v185
	v_cvt_pk_bf16_f32 v19, v188, v189
	v_cvt_pk_bf16_f32 v20, v192, v193
	v_cvt_pk_bf16_f32 v21, v196, v197
	global_store_dwordx4 v[34:35], v[18:21], off
	s_nop 1
	v_add_u32_e32 v18, 0xb0, v148
	v_ashrrev_i32_e32 v19, 31, v18
	v_lshl_add_u64 v[20:21], v[18:19], 4, s[24:25]
	global_load_dwordx4 v[20:23], v[20:21], off
	s_waitcnt vmcnt(0)
	v_mov_b32_e32 v24, v21
	v_mov_b32_e32 v25, v22
	v_mov_b32_e32 v21, v23
	v_pk_add_f32 v[20:21], v[24:25], v[20:21]
	s_nop 0
	v_add_f32_e32 v19, v20, v21
	v_fmamk_f32 v19, v19, 0x3a800000, v138
	v_rsq_f32_e32 v20, v19
	s_nop 0
	v_mad_i64_i32 v[18:19], s[0:1], v18, s4, v[144:145]
	v_lshl_add_u64 v[18:19], v[18:19], 0, v[146:147]
	v_mul_f32_e32 v198, 0xbfb8aa3b, v20
	v_mul_f32_e32 v200, v20, v20
	v_mov_b32_e32 v202, 1.0
	v_pk_mul_f32 v[182:183], v[14:15], v[198:199] op_sel_hi:[1,0]
	v_pk_mul_f32 v[186:187], v[16:17], v[198:199] op_sel_hi:[1,0]
	v_pk_mul_f32 v[190:191], v[10:11], v[198:199] op_sel_hi:[1,0]
	v_pk_mul_f32 v[194:195], v[12:13], v[198:199] op_sel_hi:[1,0]
	v_exp_f32_e32 v182, v182
	v_exp_f32_e32 v183, v183
	v_exp_f32_e32 v186, v186
	v_exp_f32_e32 v187, v187
	v_exp_f32_e32 v190, v190
	v_exp_f32_e32 v191, v191
	v_exp_f32_e32 v194, v194
	v_exp_f32_e32 v195, v195
	v_pk_mul_f32 v[184:185], v[14:15], v[6:7]
	v_pk_mul_f32 v[188:189], v[16:17], v[8:9]
	v_pk_mul_f32 v[192:193], v[10:11], v[2:3]
	v_pk_mul_f32 v[196:197], v[12:13], v[4:5]
	v_pk_add_f32 v[182:183], v[182:183], v[202:203] op_sel_hi:[1,0]
	v_pk_add_f32 v[186:187], v[186:187], v[202:203] op_sel_hi:[1,0]
	v_pk_add_f32 v[190:191], v[190:191], v[202:203] op_sel_hi:[1,0]
	v_pk_add_f32 v[194:195], v[194:195], v[202:203] op_sel_hi:[1,0]
	v_rcp_f32_e32 v182, v182
	v_rcp_f32_e32 v183, v183
	v_rcp_f32_e32 v186, v186
	v_rcp_f32_e32 v187, v187
	v_rcp_f32_e32 v190, v190
	v_rcp_f32_e32 v191, v191
	v_rcp_f32_e32 v194, v194
	v_rcp_f32_e32 v195, v195
	v_pk_mul_f32 v[184:185], v[184:185], v[200:201] op_sel_hi:[1,0]
	v_pk_mul_f32 v[188:189], v[188:189], v[200:201] op_sel_hi:[1,0]
	v_pk_mul_f32 v[192:193], v[192:193], v[200:201] op_sel_hi:[1,0]
	v_pk_mul_f32 v[196:197], v[196:197], v[200:201] op_sel_hi:[1,0]
	v_pk_mul_f32 v[184:185], v[184:185], v[182:183]
	v_pk_mul_f32 v[188:189], v[188:189], v[186:187]
	v_pk_mul_f32 v[192:193], v[192:193], v[190:191]
	v_pk_mul_f32 v[196:197], v[196:197], v[194:195]
	v_cvt_pk_bf16_f32 v2, v184, v185
	v_cvt_pk_bf16_f32 v3, v188, v189
	v_cvt_pk_bf16_f32 v4, v192, v193
	v_cvt_pk_bf16_f32 v5, v196, v197
	global_store_dwordx4 v[18:19], v[2:5], off
	s_cbranch_vccnz .LBB0_1121
	s_andn2_b64 vcc, exec, s[20:21]
	s_cbranch_vccnz .LBB0_1120
	s_barrier
	s_branch .LBB0_1120
